# gMLP mixer de-serialisation: 4 gain loads batched with the bias loads; W-row loads hoisted above the vsq wait chain
# speedup vs baseline: 1.0166x; 1.0002x over previous
.LBB0_213:
	s_lshl_b32 s24, s24, 7
	s_ashr_i32 s25, s24, 31
	s_mul_i32 s34, s6, 0x600
	s_mul_hi_i32 s8, s6, 0x600
	s_add_u32 s34, s36, s34
	s_addc_u32 s8, s37, s8
	s_lshl_b64 s[6:7], s[6:7], 11
	s_add_u32 s35, s79, s6
	s_addc_u32 s39, s80, s7
	s_lshl_b64 s[6:7], s[24:25], 2
	s_add_u32 s42, s2, s6
	s_addc_u32 s43, s3, s7
	s_add_u32 s6, s40, s47
	s_addc_u32 s7, s41, 0
	s_lshl_b64 s[2:3], s[16:17], 2
	s_add_u32 s24, s6, s2
	s_addc_u32 s25, s7, s3
	s_lshl_b64 s[6:7], s[16:17], 1
	s_add_u32 s2, s34, s6
	s_addc_u32 s3, s8, s7
	s_add_u32 s6, s35, s6
	s_addc_u32 s7, s39, s7
	s_lshl_b32 s8, s38, 2
	s_add_u32 s16, s42, s8
	s_waitcnt vmcnt(6)
	v_lshlrev_b32_e32 v64, 2, v193
	s_addc_u32 s17, s43, 0
	v_ashrrev_i32_e32 v65, 31, v64
	v_lshl_add_u64 v[64:65], v[64:65], 2, s[16:17]
	s_waitcnt vmcnt(3)
	v_lshlrev_b32_e32 v81, 2, v192
	global_load_dwordx4 v[76:79], v[64:65], off
	global_load_dwordx4 v[72:75], v[64:65], off offset:32
	global_load_dwordx4 v[68:71], v[64:65], off offset:64
	s_nop 0
	global_load_dwordx4 v[64:67], v[64:65], off offset:96
	v_lshlrev_b32_e32 v80, 11, v193
	global_load_dword v82, v81, s[24:25]
	global_load_dword v246, v81, s[24:25] offset:128
	global_load_dword v247, v81, s[24:25] offset:256
	global_load_dword v243, v81, s[24:25] offset:384
	v_add3_u32 v80, s33, v80, v81
	v_add_u32_e32 v144, s38, v147
	s_waitcnt vmcnt(0)
	v_fma_f32 v48, v48, v82, v76
	v_fma_f32 v49, v49, v82, v77
	v_fma_f32 v50, v50, v82, v78
	v_fma_f32 v51, v51, v82, v79
	v_fma_f32 v52, v52, v82, v72
	v_fma_f32 v53, v53, v82, v73
	v_fma_f32 v54, v54, v82, v74
	v_fma_f32 v55, v55, v82, v75
	v_fma_f32 v56, v56, v82, v68
	v_fma_f32 v57, v57, v82, v69
	v_fma_f32 v58, v58, v82, v70
	v_fma_f32 v59, v59, v82, v71
	v_fma_f32 v60, v60, v82, v64
	v_fma_f32 v61, v61, v82, v65
	v_fma_f32 v62, v62, v82, v66
	v_fma_f32 v63, v63, v82, v67
	v_mov_b32_e32 v82, v246
	s_waitcnt vmcnt(0)
	v_fma_f32 v32, v32, v82, v76
	ds_write2_b32 v80, v48, v32 offset1:32
	v_fma_f32 v32, v33, v82, v77
	ds_write2_b32 v80, v49, v32 offset0:128 offset1:160
	v_fma_f32 v32, v34, v82, v78
	v_add_u32_e32 v33, 0x400, v80
	ds_write2_b32 v33, v50, v32 offset1:32
	v_fma_f32 v32, v35, v82, v79
	ds_write2_b32 v33, v51, v32 offset0:128 offset1:160
	v_fma_f32 v32, v36, v82, v72
	v_add_u32_e32 v34, 0x1000, v80
	ds_write2_b32 v34, v52, v32 offset1:32
	v_fma_f32 v32, v37, v82, v73
	ds_write2_b32 v34, v53, v32 offset0:128 offset1:160
	v_fma_f32 v32, v38, v82, v74
	v_add_u32_e32 v35, 0x1400, v80
	ds_write2_b32 v35, v54, v32 offset1:32
	v_fma_f32 v32, v39, v82, v75
	ds_write2_b32 v35, v55, v32 offset0:128 offset1:160
	v_fma_f32 v32, v40, v82, v68
	v_add_u32_e32 v36, 0x2000, v80
	ds_write2_b32 v36, v56, v32 offset1:32
	v_fma_f32 v32, v41, v82, v69
	ds_write2_b32 v36, v57, v32 offset0:128 offset1:160
	v_fma_f32 v32, v42, v82, v70
	v_add_u32_e32 v37, 0x2400, v80
	ds_write2_b32 v37, v58, v32 offset1:32
	v_fma_f32 v32, v43, v82, v71
	ds_write2_b32 v37, v59, v32 offset0:128 offset1:160
	v_fma_f32 v32, v44, v82, v64
	v_add_u32_e32 v38, 0x3000, v80
	ds_write2_b32 v38, v60, v32 offset1:32
	v_fma_f32 v32, v45, v82, v65
	ds_write2_b32 v38, v61, v32 offset0:128 offset1:160
	v_fma_f32 v32, v46, v82, v66
	v_add_u32_e32 v39, 0x3400, v80
	ds_write2_b32 v39, v62, v32 offset1:32
	v_fma_f32 v32, v47, v82, v67
	ds_write2_b32 v39, v63, v32 offset0:128 offset1:160
	v_mov_b32_e32 v32, v247
	s_waitcnt vmcnt(0)
	v_fma_f32 v16, v16, v32, v76
	v_fma_f32 v17, v17, v32, v77
	v_fma_f32 v18, v18, v32, v78
	v_fma_f32 v19, v19, v32, v79
	v_fma_f32 v20, v20, v32, v72
	v_fma_f32 v21, v21, v32, v73
	v_fma_f32 v22, v22, v32, v74
	v_fma_f32 v23, v23, v32, v75
	v_fma_f32 v24, v24, v32, v68
	v_fma_f32 v25, v25, v32, v69
	v_fma_f32 v26, v26, v32, v70
	v_fma_f32 v27, v27, v32, v71
	v_fma_f32 v28, v28, v32, v64
	v_fma_f32 v29, v29, v32, v65
	v_fma_f32 v30, v30, v32, v66
	v_fma_f32 v31, v31, v32, v67
	v_mov_b32_e32 v32, v243
	s_waitcnt vmcnt(0)
	v_fma_f32 v0, v0, v32, v76
	ds_write2_b32 v80, v16, v0 offset0:64 offset1:96
	v_fma_f32 v0, v1, v32, v77
	ds_write2_b32 v80, v17, v0 offset0:192 offset1:224
	v_fma_f32 v0, v2, v32, v78
	ds_write2_b32 v33, v18, v0 offset0:64 offset1:96
	v_fma_f32 v0, v4, v32, v72
	ds_write2_b32 v34, v20, v0 offset0:64 offset1:96
	v_fma_f32 v0, v5, v32, v73
	ds_write2_b32 v34, v21, v0 offset0:192 offset1:224
	v_fma_f32 v0, v6, v32, v74
	ds_write2_b32 v35, v22, v0 offset0:64 offset1:96
	v_fma_f32 v0, v8, v32, v68
	ds_write2_b32 v36, v24, v0 offset0:64 offset1:96
	v_fma_f32 v0, v9, v32, v69
	ds_write2_b32 v36, v25, v0 offset0:192 offset1:224
	v_fma_f32 v0, v10, v32, v70
	ds_write2_b32 v37, v26, v0 offset0:64 offset1:96
	v_fma_f32 v0, v12, v32, v64
	ds_write2_b32 v38, v28, v0 offset0:64 offset1:96
	v_fma_f32 v0, v13, v32, v65
	ds_write2_b32 v38, v29, v0 offset0:192 offset1:224
	v_fma_f32 v0, v14, v32, v66
	ds_write2_b32 v39, v30, v0 offset0:64 offset1:96
	v_lshl_add_u64 v[0:1], s[2:3], 0, v[158:159]
	v_fmac_f32_e32 v79, v3, v32
	v_mad_i64_i32 v[2:3], s[2:3], v148, s69, v[0:1]
	v_fmac_f32_e32 v71, v11, v32
	global_load_dwordx4 v[8:11], v[2:3], off
	v_add_u32_e32 v96, s38, v205
	v_mad_i64_i32 v[98:99], s[2:3], v96, s69, v[0:1]
	global_load_dwordx4 v[100:103], v[98:99], off
	v_add_u32_e32 v96, s38, v202
	v_mad_i64_i32 v[98:99], s[2:3], v96, s69, v[0:1]
	global_load_dwordx4 v[104:107], v[98:99], off
	v_add_u32_e32 v96, s38, v201
	v_mad_i64_i32 v[98:99], s[2:3], v96, s69, v[0:1]
	global_load_dwordx4 v[108:111], v[98:99], off
	v_add_u32_e32 v96, s38, v200
	v_mad_i64_i32 v[98:99], s[2:3], v96, s69, v[0:1]
	global_load_dwordx4 v[112:115], v[98:99], off
	v_add_u32_e32 v96, s38, v199
	v_mad_i64_i32 v[98:99], s[2:3], v96, s69, v[0:1]
	global_load_dwordx4 v[116:119], v[98:99], off
	v_add_u32_e32 v96, s38, v145
	v_mad_i64_i32 v[98:99], s[2:3], v96, s69, v[0:1]
	global_load_dwordx4 v[120:123], v[98:99], off
	v_fmac_f32_e32 v75, v7, v32
	v_fmac_f32_e32 v67, v15, v32
	v_lshl_add_u32 v6, v149, 5, s33
	ds_write2_b32 v33, v19, v79 offset0:192 offset1:224
	ds_write2_b32 v35, v23, v75 offset0:192 offset1:224
	ds_write2_b32 v37, v27, v71 offset0:192 offset1:224
	ds_write2_b32 v39, v31, v67 offset0:192 offset1:224
	v_lshl_add_u32 v2, v213, 9, v6
	ds_read_b128 v[12:15], v2
	ds_read_b128 v[16:19], v2 offset:16
	v_ashrrev_i32_e32 v149, 31, v148
	v_lshl_add_u64 v[4:5], s[6:7], 0, v[158:159]
	v_lshl_add_u32 v7, v205, 9, v6
	s_waitcnt vmcnt(6)
	v_lshlrev_b32_e32 v2, 16, v8
	v_and_b32_e32 v3, 0xffff0000, v8
	s_waitcnt lgkmcnt(1)
	v_pk_mul_f32 v[2:3], v[12:13], v[2:3]
	s_nop 0
	v_cvt_pk_bf16_f32 v8, v2, v3
	v_lshlrev_b32_e32 v2, 16, v9
	v_and_b32_e32 v3, 0xffff0000, v9
	v_pk_mul_f32 v[2:3], v[14:15], v[2:3]
	s_nop 0
	v_cvt_pk_bf16_f32 v9, v2, v3
	v_lshlrev_b32_e32 v2, 16, v10
	v_and_b32_e32 v3, 0xffff0000, v10
	s_waitcnt lgkmcnt(0)
	v_pk_mul_f32 v[2:3], v[16:17], v[2:3]
	s_nop 0
	v_cvt_pk_bf16_f32 v10, v2, v3
	v_lshlrev_b32_e32 v2, 16, v11
	v_and_b32_e32 v3, 0xffff0000, v11
	v_pk_mul_f32 v[2:3], v[18:19], v[2:3]
	s_nop 0
	v_cvt_pk_bf16_f32 v11, v2, v3
	v_lshlrev_b64 v[2:3], 11, v[148:149]
	v_lshl_add_u64 v[2:3], v[4:5], 0, v[2:3]
	global_store_dwordx4 v[2:3], v[8:11], off sc1
	v_add_u32_e32 v2, s38, v205
	v_ashrrev_i32_e32 v3, 31, v2
	ds_read_b128 v[12:15], v7
	ds_read_b128 v[16:19], v7 offset:16
	v_lshlrev_b64 v[2:3], 11, v[2:3]
	v_lshl_add_u64 v[2:3], v[4:5], 0, v[2:3]
	v_lshl_add_u32 v7, v202, 9, v6
	s_waitcnt vmcnt(6)
	v_mov_b32_e32 v8, v100
	v_mov_b32_e32 v9, v101
	v_mov_b32_e32 v10, v102
	v_mov_b32_e32 v11, v103
	v_lshlrev_b32_e32 v20, 16, v8
	v_and_b32_e32 v21, 0xffff0000, v8
	s_waitcnt lgkmcnt(1)
	v_pk_mul_f32 v[12:13], v[12:13], v[20:21]
	s_nop 0
	v_cvt_pk_bf16_f32 v8, v12, v13
	v_lshlrev_b32_e32 v12, 16, v9
	v_and_b32_e32 v13, 0xffff0000, v9
	v_pk_mul_f32 v[12:13], v[14:15], v[12:13]
	s_nop 0
	v_cvt_pk_bf16_f32 v9, v12, v13
	v_lshlrev_b32_e32 v12, 16, v10
	v_and_b32_e32 v13, 0xffff0000, v10
	s_waitcnt lgkmcnt(0)
	v_pk_mul_f32 v[12:13], v[16:17], v[12:13]
	s_nop 0
	v_cvt_pk_bf16_f32 v10, v12, v13
	v_lshlrev_b32_e32 v12, 16, v11
	v_and_b32_e32 v13, 0xffff0000, v11
	v_pk_mul_f32 v[12:13], v[18:19], v[12:13]
	s_nop 0
	v_cvt_pk_bf16_f32 v11, v12, v13
	global_store_dwordx4 v[2:3], v[8:11], off sc1
	v_add_u32_e32 v2, s38, v202
	v_ashrrev_i32_e32 v3, 31, v2
	ds_read_b128 v[12:15], v7
	ds_read_b128 v[16:19], v7 offset:16
	v_lshlrev_b64 v[2:3], 11, v[2:3]
	v_lshl_add_u64 v[2:3], v[4:5], 0, v[2:3]
	v_lshl_add_u32 v7, v201, 9, v6
	s_waitcnt vmcnt(6)
	v_mov_b32_e32 v8, v104
	v_mov_b32_e32 v9, v105
	v_mov_b32_e32 v10, v106
	v_mov_b32_e32 v11, v107
	v_lshlrev_b32_e32 v20, 16, v8
	v_and_b32_e32 v21, 0xffff0000, v8
	s_waitcnt lgkmcnt(1)
	v_pk_mul_f32 v[12:13], v[12:13], v[20:21]
	s_nop 0
	v_cvt_pk_bf16_f32 v8, v12, v13
	v_lshlrev_b32_e32 v12, 16, v9
	v_and_b32_e32 v13, 0xffff0000, v9
	v_pk_mul_f32 v[12:13], v[14:15], v[12:13]
	s_nop 0
	v_cvt_pk_bf16_f32 v9, v12, v13
	v_lshlrev_b32_e32 v12, 16, v10
	v_and_b32_e32 v13, 0xffff0000, v10
	s_waitcnt lgkmcnt(0)
	v_pk_mul_f32 v[12:13], v[16:17], v[12:13]
	s_nop 0
	v_cvt_pk_bf16_f32 v10, v12, v13
	v_lshlrev_b32_e32 v12, 16, v11
	v_and_b32_e32 v13, 0xffff0000, v11
	v_pk_mul_f32 v[12:13], v[18:19], v[12:13]
	s_nop 0
	v_cvt_pk_bf16_f32 v11, v12, v13
	global_store_dwordx4 v[2:3], v[8:11], off sc1
	v_add_u32_e32 v2, s38, v201
	v_ashrrev_i32_e32 v3, 31, v2
	ds_read_b128 v[12:15], v7
	ds_read_b128 v[16:19], v7 offset:16
	v_lshlrev_b64 v[2:3], 11, v[2:3]
	v_lshl_add_u64 v[2:3], v[4:5], 0, v[2:3]
	v_lshl_add_u32 v7, v200, 9, v6
	s_waitcnt vmcnt(6)
	v_mov_b32_e32 v8, v108
	v_mov_b32_e32 v9, v109
	v_mov_b32_e32 v10, v110
	v_mov_b32_e32 v11, v111
	v_lshlrev_b32_e32 v20, 16, v8
	v_and_b32_e32 v21, 0xffff0000, v8
	s_waitcnt lgkmcnt(1)
	v_pk_mul_f32 v[12:13], v[12:13], v[20:21]
	s_nop 0
	v_cvt_pk_bf16_f32 v8, v12, v13
	v_lshlrev_b32_e32 v12, 16, v9
	v_and_b32_e32 v13, 0xffff0000, v9
	v_pk_mul_f32 v[12:13], v[14:15], v[12:13]
	s_nop 0
	v_cvt_pk_bf16_f32 v9, v12, v13
	v_lshlrev_b32_e32 v12, 16, v10
	v_and_b32_e32 v13, 0xffff0000, v10
	s_waitcnt lgkmcnt(0)
	v_pk_mul_f32 v[12:13], v[16:17], v[12:13]
	s_nop 0
	v_cvt_pk_bf16_f32 v10, v12, v13
	v_lshlrev_b32_e32 v12, 16, v11
	v_and_b32_e32 v13, 0xffff0000, v11
	v_pk_mul_f32 v[12:13], v[18:19], v[12:13]
	s_nop 0
	v_cvt_pk_bf16_f32 v11, v12, v13
	global_store_dwordx4 v[2:3], v[8:11], off sc1
	v_add_u32_e32 v2, s38, v200
	v_ashrrev_i32_e32 v3, 31, v2
	ds_read_b128 v[12:15], v7
	ds_read_b128 v[16:19], v7 offset:16
	v_lshlrev_b64 v[2:3], 11, v[2:3]
	v_lshl_add_u64 v[2:3], v[4:5], 0, v[2:3]
	v_lshl_add_u32 v7, v199, 9, v6
	s_waitcnt vmcnt(6)
	v_mov_b32_e32 v8, v112
	v_mov_b32_e32 v9, v113
	v_mov_b32_e32 v10, v114
	v_mov_b32_e32 v11, v115
	v_lshlrev_b32_e32 v20, 16, v8
	v_and_b32_e32 v21, 0xffff0000, v8
	s_waitcnt lgkmcnt(1)
	v_pk_mul_f32 v[12:13], v[12:13], v[20:21]
	s_nop 0
	v_cvt_pk_bf16_f32 v8, v12, v13
	v_lshlrev_b32_e32 v12, 16, v9
	v_and_b32_e32 v13, 0xffff0000, v9
	v_pk_mul_f32 v[12:13], v[14:15], v[12:13]
	s_nop 0
	v_cvt_pk_bf16_f32 v9, v12, v13
	v_lshlrev_b32_e32 v12, 16, v10
	v_and_b32_e32 v13, 0xffff0000, v10
	s_waitcnt lgkmcnt(0)
	v_pk_mul_f32 v[12:13], v[16:17], v[12:13]
	s_nop 0
	v_cvt_pk_bf16_f32 v10, v12, v13
	v_lshlrev_b32_e32 v12, 16, v11
	v_and_b32_e32 v13, 0xffff0000, v11
	v_pk_mul_f32 v[12:13], v[18:19], v[12:13]
	s_nop 0
	v_cvt_pk_bf16_f32 v11, v12, v13
	global_store_dwordx4 v[2:3], v[8:11], off sc1
	v_add_u32_e32 v2, s38, v199
	v_ashrrev_i32_e32 v3, 31, v2
	ds_read_b128 v[12:15], v7
	ds_read_b128 v[16:19], v7 offset:16
	v_lshlrev_b64 v[2:3], 11, v[2:3]
	v_lshl_add_u64 v[2:3], v[4:5], 0, v[2:3]
	v_lshl_add_u32 v7, v145, 9, v6
	s_waitcnt vmcnt(6)
	v_mov_b32_e32 v8, v116
	v_mov_b32_e32 v9, v117
	v_mov_b32_e32 v10, v118
	v_mov_b32_e32 v11, v119
	v_lshlrev_b32_e32 v20, 16, v8
	v_and_b32_e32 v21, 0xffff0000, v8
	s_waitcnt lgkmcnt(1)
	v_pk_mul_f32 v[12:13], v[12:13], v[20:21]
	s_nop 0
	v_cvt_pk_bf16_f32 v8, v12, v13
	v_lshlrev_b32_e32 v12, 16, v9
	v_and_b32_e32 v13, 0xffff0000, v9
	v_pk_mul_f32 v[12:13], v[14:15], v[12:13]
	s_nop 0
	v_cvt_pk_bf16_f32 v9, v12, v13
	v_lshlrev_b32_e32 v12, 16, v10
	v_and_b32_e32 v13, 0xffff0000, v10
	s_waitcnt lgkmcnt(0)
	v_pk_mul_f32 v[12:13], v[16:17], v[12:13]
	s_nop 0
	v_cvt_pk_bf16_f32 v10, v12, v13
	v_lshlrev_b32_e32 v12, 16, v11
	v_and_b32_e32 v13, 0xffff0000, v11
	v_pk_mul_f32 v[12:13], v[18:19], v[12:13]
	s_nop 0
	v_cvt_pk_bf16_f32 v11, v12, v13
	global_store_dwordx4 v[2:3], v[8:11], off sc1
	v_add_u32_e32 v2, s38, v145
	v_ashrrev_i32_e32 v3, 31, v2
	ds_read_b128 v[12:15], v7
	ds_read_b128 v[16:19], v7 offset:16
	v_lshlrev_b64 v[2:3], 11, v[2:3]
	v_lshl_add_u64 v[2:3], v[4:5], 0, v[2:3]
	v_mad_i64_i32 v[0:1], s[2:3], v144, s69, v[0:1]
	v_ashrrev_i32_e32 v145, 31, v144
	s_waitcnt vmcnt(6)
	v_mov_b32_e32 v8, v120
	v_mov_b32_e32 v9, v121
	v_mov_b32_e32 v10, v122
	v_mov_b32_e32 v11, v123
	v_lshlrev_b32_e32 v20, 16, v8
	v_and_b32_e32 v21, 0xffff0000, v8
	s_waitcnt lgkmcnt(1)
	v_pk_mul_f32 v[12:13], v[12:13], v[20:21]
	s_nop 0
	v_cvt_pk_bf16_f32 v8, v12, v13
	v_lshlrev_b32_e32 v12, 16, v9
	v_and_b32_e32 v13, 0xffff0000, v9
	v_pk_mul_f32 v[12:13], v[14:15], v[12:13]
	s_nop 0
	v_cvt_pk_bf16_f32 v9, v12, v13
	v_lshlrev_b32_e32 v12, 16, v10
	v_and_b32_e32 v13, 0xffff0000, v10
	s_waitcnt lgkmcnt(0)
	v_pk_mul_f32 v[12:13], v[16:17], v[12:13]
	s_nop 0
	v_cvt_pk_bf16_f32 v10, v12, v13
	v_lshlrev_b32_e32 v12, 16, v11
	v_and_b32_e32 v13, 0xffff0000, v11
	v_pk_mul_f32 v[12:13], v[18:19], v[12:13]
	s_nop 0
	v_cvt_pk_bf16_f32 v11, v12, v13
	global_store_dwordx4 v[2:3], v[8:11], off sc1
	global_load_dwordx4 v[0:3], v[0:1], off
	s_waitcnt vmcnt(0)
	v_lshlrev_b32_e32 v14, 16, v0
	v_lshl_add_u32 v10, v147, 9, v6
	ds_read_b128 v[6:9], v10
	ds_read_b128 v[10:13], v10 offset:16
	v_and_b32_e32 v15, 0xffff0000, v0
	s_waitcnt lgkmcnt(1)
	v_pk_mul_f32 v[6:7], v[6:7], v[14:15]
	s_nop 0
	v_cvt_pk_bf16_f32 v0, v6, v7
	v_lshlrev_b32_e32 v6, 16, v1
	v_and_b32_e32 v7, 0xffff0000, v1
	v_pk_mul_f32 v[6:7], v[8:9], v[6:7]
	s_nop 0
	v_cvt_pk_bf16_f32 v1, v6, v7
	v_lshlrev_b32_e32 v6, 16, v2
	v_and_b32_e32 v7, 0xffff0000, v2
	s_waitcnt lgkmcnt(0)
	v_pk_mul_f32 v[6:7], v[10:11], v[6:7]
	s_nop 0
	v_cvt_pk_bf16_f32 v2, v6, v7
	v_lshlrev_b32_e32 v6, 16, v3
	v_and_b32_e32 v7, 0xffff0000, v3
	v_pk_mul_f32 v[6:7], v[12:13], v[6:7]
	s_nop 0
	v_cvt_pk_bf16_f32 v3, v6, v7

.LBB0_222:
	s_and_b64 vcc, exec, s[2:3]
	s_cbranch_vccz .LBB0_214
	s_mul_hi_i32 s2, s49, 0x2aaaaaab
	s_lshr_b32 s3, s2, 31
	s_ashr_i32 s2, s2, 2
	s_add_i32 s7, s2, s3
	s_mul_i32 s2, s7, 24
	s_sub_i32 s2, s49, s2
	s_ashr_i32 s8, s2, 2
	s_and_b32 s50, s2, 3
	s_and_b32 s2, s7, 63
	s_lshl_b32 s3, s7, 7
	s_lshl_b32 s2, s2, 7
	s_and_b32 s3, s3, 0xffffe000
	s_or_b32 s6, s3, s2
	s_load_dwordx4 s[40:43], s[0:1], 0x70
	s_load_dwordx2 s[2:3], s[0:1], 0x80
	s_mul_i32 s16, s75, 6
	s_add_i32 s24, s8, s16
	s_ashr_i32 s25, s24, 31
	s_lshl_b64 s[16:17], s[24:25], 16
	s_waitcnt lgkmcnt(0)
	s_add_u32 s34, s42, s16
	s_addc_u32 s35, s43, s17
	s_lshl_b32 s16, s8, 7
	s_ashr_i32 s17, s16, 31
	s_mul_hi_i32 s8, s7, 0x300
	s_mulk_i32 s7, 0x300
	s_add_u32 s38, s7, s16
	s_addc_u32 s39, s8, s17
	s_lshl_b64 s[38:39], s[38:39], 8
	s_add_u32 s38, s12, s38
	s_addc_u32 s39, s13, s39
	s_ashr_i32 s7, s6, 31
	s_lshl_b64 s[42:43], s[6:7], 3
	s_add_u32 s42, s45, s42
	s_waitcnt vmcnt(0)
	v_lshlrev_b32_e32 v0, 1, v207
	s_addc_u32 s43, s46, s43
	v_ashrrev_i32_e32 v1, 31, v0
	v_lshl_add_u64 v[0:1], v[0:1], 3, s[42:43]
	global_load_dwordx4 v[0:3], v[0:1], off
	v_lshlrev_b64 v[4:5], 8, v[148:149]
	v_lshlrev_b32_e32 v10, 4, v207
	v_and_b32_e32 v158, 0x70, v10
	v_lshl_add_u64 v[4:5], s[38:39], 0, v[4:5]
	v_lshl_add_u64 v[150:151], v[4:5], 0, v[158:159]
	v_add_co_u32_e32 v4, vcc, s68, v150
	global_load_dwordx4 v[68:71], v[150:151], off
	global_load_dwordx4 v[64:67], v[150:151], off offset:2048
	v_addc_co_u32_e32 v5, vcc, 0, v151, vcc
	v_add_co_u32_e32 v6, vcc, s23, v150
	v_ashrrev_i32_e32 v213, 4, v207
	s_nop 0
	v_addc_co_u32_e32 v7, vcc, 0, v151, vcc
	v_add_co_u32_e32 v8, vcc, s53, v150
	s_lshl_b32 s38, s50, 5
	s_nop 0
	v_addc_co_u32_e32 v9, vcc, 0, v151, vcc
	global_load_dwordx4 v[92:95], v[8:9], off offset:-4096
	global_load_dwordx4 v[80:83], v[8:9], off
	global_load_dwordx4 v[72:75], v[8:9], off offset:2048
	global_load_dwordx4 v[88:91], v[6:7], off offset:2048
	global_load_dwordx4 v[76:79], v[4:5], off
	v_add_u32_e32 v148, s38, v213
	global_load_dwordx4 v[84:87], v[4:5], off offset:2048
	v_lshlrev_b32_e32 v4, 7, v148
	v_and_b32_e32 v149, 15, v207
	v_ashrrev_i32_e32 v5, 31, v4
	v_lshlrev_b32_e32 v158, 4, v149
	v_lshl_add_u64 v[4:5], v[4:5], 2, s[34:35]
	v_lshl_add_u64 v[152:153], v[4:5], 0, v[158:159]
	v_add_co_u32_e32 v4, vcc, s23, v152
	v_lshl_add_u32 v11, v207, 3, s55
	s_nop 0
	v_addc_co_u32_e32 v5, vcc, 0, v153, vcc
	v_add_co_u32_e32 v6, vcc, s53, v152
	s_mov_b64 s[34:35], 0x1080
	s_nop 0
	v_addc_co_u32_e32 v7, vcc, 0, v153, vcc
	v_lshl_add_u64 v[154:155], v[150:151], 0, s[34:35]
	s_mov_b64 s[34:35], 0x1880
	v_add_u32_e32 v205, 4, v213
	v_add_u32_e32 v201, 12, v213
	v_add_u32_e32 v199, 20, v213
	v_add_u32_e32 v147, 28, v213
	v_add_co_u32_e32 v244, vcc, s68, v152
	s_nop 1
	v_addc_co_u32_e32 v245, vcc, 0, v153, vcc
	global_load_dwordx4 v[96:99], v[152:153], off
	global_load_dwordx4 v[100:103], v[152:153], off offset:2048
	global_load_dwordx4 v[104:107], v[6:7], off
	global_load_dwordx4 v[112:115], v[6:7], off offset:2048
	global_load_dwordx4 v[108:111], v[4:5], off offset:2048
	global_load_dwordx4 v[120:123], v[244:245], off
	global_load_dwordx4 v[116:119], v[6:7], off offset:-4096
	global_load_dwordx4 v[124:127], v[244:245], off offset:2048
	v_add_u32_e32 v22, 4, v212
	v_add_u32_e32 v23, 5, v212
	v_xor_b32_e32 v14, v201, v207
	v_xor_b32_e32 v17, v199, v207
	v_xor_b32_e32 v19, v147, v207
	v_xor_b32_e32 v20, v212, v207
	v_bitop3_b32 v21, v212, v207, 1 bitop3:0x36
	v_xor_b32_e32 v22, v22, v207
	v_xor_b32_e32 v23, v23, v207
	v_xor_b32_e32 v28, v193, v206
	v_xor_b32_e32 v30, v209, v206
	v_xor_b32_e32 v31, v208, v206
	v_add_u32_e32 v202, 8, v213
	v_lshlrev_b32_e32 v14, 4, v14
	v_add_u32_e32 v200, 16, v213
	v_lshlrev_b32_e32 v17, 4, v17
	v_add_u32_e32 v145, 24, v213
	v_lshlrev_b32_e32 v19, 4, v19
	v_lshlrev_b32_e32 v20, 4, v20
	v_lshlrev_b32_e32 v21, 4, v21
	v_lshlrev_b32_e32 v22, 4, v22
	v_lshlrev_b32_e32 v23, 4, v23
	v_lshlrev_b32_e32 v28, 4, v28
	v_lshlrev_b32_e32 v30, 4, v30
	v_lshlrev_b32_e32 v31, 4, v31
	s_mov_b32 s8, 0
	s_cmp_lt_u32 s50, 2
	v_and_b32_e32 v14, 0x70, v14
	v_and_b32_e32 v17, 0x70, v17
	v_and_b32_e32 v19, 0x70, v19
	v_and_b32_e32 v20, 0x70, v20
	v_and_b32_e32 v21, 0x70, v21
	v_and_b32_e32 v22, 0x70, v22
	v_and_b32_e32 v23, 0x70, v23
	s_waitcnt vmcnt(16)
	v_xor_b32_e32 v8, v0, v1
	v_xor_b32_e32 v12, v2, v3
	v_ffbh_i32_e32 v9, v1
	v_ffbh_i32_e32 v13, v3
	v_ashrrev_i32_e32 v8, 31, v8
	v_ashrrev_i32_e32 v12, 31, v12
	v_add_u32_e32 v9, -1, v9
	v_add_u32_e32 v13, -1, v13
	v_add_u32_e32 v8, 32, v8
	v_add_u32_e32 v12, 32, v12
	v_min_u32_e32 v8, v9, v8
	v_min_u32_e32 v9, v13, v12
	v_lshlrev_b64 v[0:1], v8, v[0:1]
	v_lshlrev_b64 v[2:3], v9, v[2:3]
	v_min_u32_e32 v0, 1, v0
	v_min_u32_e32 v2, 1, v2
	v_or_b32_e32 v0, v1, v0
	v_or_b32_e32 v1, v3, v2
	v_cvt_f32_i32_e32 v0, v0
	v_cvt_f32_i32_e32 v1, v1
	v_sub_u32_e32 v2, 32, v8
	v_sub_u32_e32 v3, 32, v9
	v_ldexp_f32 v0, v0, v2
	v_ldexp_f32 v1, v1, v3
	v_mul_f32_e32 v0, 0x35800000, v0
	v_mul_f32_e32 v1, 0x35800000, v1
	v_fmamk_f32 v0, v0, 0x3aaaaaab, v195
	v_fmamk_f32 v1, v1, 0x3aaaaaab, v195
	v_rsq_f32_e32 v0, v0
	v_rsq_f32_e32 v1, v1
	v_add_co_u32_e32 v2, vcc, s68, v152
	v_xor_b32_e32 v9, v213, v207
	ds_write_b64 v11, v[0:1]
	s_waitcnt lgkmcnt(0)
	v_addc_co_u32_e32 v3, vcc, 0, v153, vcc
	v_xor_b32_e32 v3, v168, v207
	v_lshl_add_u64 v[168:169], v[150:151], 0, s[34:35]
	s_mov_b64 s[34:35], 0x2080
	v_lshl_add_u64 v[170:171], v[150:151], 0, s[34:35]
	s_mov_b64 s[34:35], 0x2880
	v_lshl_add_u64 v[172:173], v[150:151], 0, s[34:35]
	s_mov_b64 s[34:35], 0x3080
	v_lshl_add_u64 v[174:175], v[150:151], 0, s[34:35]
	s_mov_b64 s[34:35], 0x3880
	v_lshl_add_u64 v[176:177], v[150:151], 0, s[34:35]
	s_mov_b64 s[34:35], 0x4000
	v_lshl_add_u64 v[178:179], v[150:151], 0, s[34:35]
	s_mov_b64 s[34:35], 0x1100
	v_lshl_add_u64 v[180:181], v[152:153], 0, s[34:35]
	s_mov_b64 s[34:35], 0x1900
	v_lshrrev_b32_e32 v4, 1, v146
	v_lshrrev_b32_e32 v5, 1, v144
	v_lshrrev_b32_e32 v6, 1, v210
	v_lshrrev_b32_e32 v7, 1, v211
	v_lshl_add_u64 v[182:183], v[152:153], 0, s[34:35]
	s_mov_b64 s[34:35], 0x2100
	v_and_b32_e32 v0, 0x80, v10
	v_xor_b32_e32 v4, v4, v207
	v_xor_b32_e32 v5, v5, v207
	v_xor_b32_e32 v6, v6, v207
	v_xor_b32_e32 v7, v7, v207
	v_xor_b32_e32 v11, v205, v207
	v_lshl_add_u64 v[184:185], v[152:153], 0, s[34:35]
	s_mov_b64 s[34:35], 0x2900
	v_add_u32_e32 v0, s33, v0
	v_lshlrev_b32_e32 v3, 4, v3
	v_lshlrev_b32_e32 v4, 4, v4
	v_lshlrev_b32_e32 v5, 4, v5
	v_lshlrev_b32_e32 v6, 4, v6
	v_lshlrev_b32_e32 v7, 4, v7
	v_lshlrev_b32_e32 v9, 4, v9
	v_lshlrev_b32_e32 v11, 4, v11
	v_lshl_add_u64 v[186:187], v[152:153], 0, s[34:35]
	s_mov_b64 s[34:35], 0x3100
	v_lshl_add_u32 v1, v192, 8, s33
	v_and_b32_e32 v2, 0xffffffe0, v207
	v_and_b32_e32 v3, 0x70, v3
	v_and_b32_e32 v4, 0x70, v4
	v_and_b32_e32 v5, 0x70, v5
	v_and_b32_e32 v6, 0x70, v6
	v_and_b32_e32 v7, 0x70, v7
	v_lshl_add_u32 v8, v213, 8, v0
	v_and_b32_e32 v9, 0x70, v9
	v_lshl_add_u32 v10, v205, 8, v0
	v_and_b32_e32 v11, 0x70, v11
	v_lshl_add_u32 v12, v202, 8, v0
	v_lshl_add_u32 v13, v201, 8, v0
	v_lshl_add_u32 v15, v200, 8, v0
	v_lshl_add_u32 v16, v199, 8, v0
	v_lshl_add_u32 v18, v145, 8, v0
	v_lshl_add_u32 v0, v147, 8, v0
	v_lshl_add_u64 v[188:189], v[152:153], 0, s[34:35]
	s_mov_b64 s[34:35], 0x3900
	v_lshl_add_u32 v24, v146, 7, s33
	v_lshl_add_u32 v25, v144, 7, s33
	v_lshl_add_u32 v26, v210, 7, s33
	v_lshl_add_u32 v27, v211, 7, s33
	v_and_b32_e32 v29, 0x70, v28
	v_and_b32_e32 v30, 0x70, v30
	v_bitop3_b32 v28, v28, 64, v197 bitop3:0x6c
	v_and_b32_e32 v31, 0x70, v31
	v_mov_b32_e32 v48, 0
	s_cselect_b32 s25, 1, 2
	v_lshl_add_u64 v[190:191], v[152:153], 0, s[34:35]
	v_add_u32_e32 v144, s55, v2
	v_add_u32_e32 v146, v8, v9
	v_add_u32_e32 v206, v10, v11
	v_add_u32_e32 v207, v12, v9
	v_add_u32_e32 v208, v13, v14
	v_add_u32_e32 v209, v15, v9
	v_add_u32_e32 v210, v16, v17
	v_add_u32_e32 v211, v18, v9
	v_add_u32_e32 v212, v0, v19
	v_add_u32_e32 v214, v1, v20
	v_add_u32_e32 v215, v1, v21
	v_add_u32_e32 v216, v1, v22
	v_add_u32_e32 v217, v1, v23
	v_add_u32_e32 v204, v204, v3
	v_add_u32_e32 v218, v24, v4
	v_add_u32_e32 v219, v25, v5
	v_add_u32_e32 v220, v26, v6
	v_add_u32_e32 v221, v27, v7
	v_add_u32_e32 v222, v203, v29
	v_add_u32_e32 v223, v203, v30
	v_add_u32_e32 v224, v203, v28
	v_add_u32_e32 v203, v203, v31
	s_mov_b32 s39, s8
	v_mov_b32_e32 v49, v48
	v_mov_b32_e32 v50, v48
	v_mov_b32_e32 v51, v48
	v_mov_b32_e32 v52, v48
	v_mov_b32_e32 v53, v48
	v_mov_b32_e32 v54, v48
	v_mov_b32_e32 v55, v48
	v_mov_b32_e32 v56, v48
	v_mov_b32_e32 v57, v48
	v_mov_b32_e32 v58, v48
	v_mov_b32_e32 v59, v48
	v_mov_b32_e32 v60, v48
	v_mov_b32_e32 v61, v48
	v_mov_b32_e32 v62, v48
	v_mov_b32_e32 v63, v48
	v_mov_b32_e32 v32, v48
	v_mov_b32_e32 v33, v48
	v_mov_b32_e32 v34, v48
	v_mov_b32_e32 v35, v48
	v_mov_b32_e32 v36, v48
	v_mov_b32_e32 v37, v48
	v_mov_b32_e32 v38, v48
	v_mov_b32_e32 v39, v48
	v_mov_b32_e32 v40, v48
	v_mov_b32_e32 v41, v48
	v_mov_b32_e32 v42, v48
	v_mov_b32_e32 v43, v48
	v_mov_b32_e32 v44, v48
	v_mov_b32_e32 v45, v48
	v_mov_b32_e32 v46, v48
	v_mov_b32_e32 v47, v48
	v_mov_b32_e32 v16, v48
	v_mov_b32_e32 v17, v48
	v_mov_b32_e32 v18, v48
	v_mov_b32_e32 v19, v48
	v_mov_b32_e32 v20, v48
	v_mov_b32_e32 v21, v48
	v_mov_b32_e32 v22, v48
	v_mov_b32_e32 v23, v48
	v_mov_b32_e32 v24, v48
	v_mov_b32_e32 v25, v48
	v_mov_b32_e32 v26, v48
	v_mov_b32_e32 v27, v48
	v_mov_b32_e32 v28, v48
	v_mov_b32_e32 v29, v48
	v_mov_b32_e32 v30, v48
	v_mov_b32_e32 v31, v48
	v_mov_b32_e32 v0, v48
	v_mov_b32_e32 v1, v48
	v_mov_b32_e32 v2, v48
	v_mov_b32_e32 v3, v48
	v_mov_b32_e32 v4, v48
	v_mov_b32_e32 v5, v48
	v_mov_b32_e32 v6, v48
	v_mov_b32_e32 v7, v48
	v_mov_b32_e32 v8, v48
	v_mov_b32_e32 v9, v48
	v_mov_b32_e32 v10, v48
	v_mov_b32_e32 v11, v48
	v_mov_b32_e32 v12, v48
	v_mov_b32_e32 v13, v48
	v_mov_b32_e32 v14, v48
	v_mov_b32_e32 v15, v48
	s_branch .LBB0_225
